# atomic fan-out: split-K sample tails run on 4x (G2) / 8x (G4) as many WGs, each issuing 1/F of the tile's f32 atomics
# speedup vs baseline: 1.0235x; 1.0176x over previous
.LBB0_542:
	s_mul_i32 s8, s2, 0x5d2
	s_lshr_b32 s8, s8, 16
	s_mul_i32 s9, s8, 44
	s_sub_u32 s38, s2, s9
	s_and_b32 s39, s38, 3
	s_lshr_b32 s38, s38, 2
	s_lshl_b32 s38, s38, 9
	s_mov_b32 s9, 0
	v_writelane_b32 v254, s38, 15
	v_writelane_b32 v254, s9, 16
	s_mul_i32 s8, s39, 0x160000
	v_writelane_b32 v254, s8, 13
	v_writelane_b32 v254, s9, 14
	s_lshl_b32 s8, s39, 8
	v_writelane_b32 v254, s8, 17
	s_load_dwordx2 s[8:9], s[76:77], 0xd0
	s_waitcnt lgkmcnt(0)
	s_add_u32 s8, s8, s38
	s_addc_u32 s9, s9, 0
	s_add_u32 s82, s8, 0x1c800000
	s_addc_u32 s83, s9, 0
	s_add_u32 s34, s8, 0x1c8b0000
	s_addc_u32 s35, s9, 0
	s_cmp_lt_u32 s2, 176
	s_cselect_b64 s[8:9], -1, 0
	v_writelane_b32 v254, s8, 11
	v_writelane_b32 v254, s9, 12
	s_nop 1
	v_readlane_b32 s8, v254, 11
	v_mov_b32_e32 v2, v204
	v_readlane_b32 s9, v254, 12
	s_andn2_b64 vcc, exec, s[8:9]
	v_readfirstlane_b32 s52, v2
	s_cbranch_vccnz .LBB0_550
	v_lshlrev_b32_e32 v0, 4, v2
	v_add_u32_e32 v3, 0x2000, v0
	v_ashrrev_i32_e32 v4, 31, v3
	v_lshrrev_b32_e32 v4, 22, v4
	v_add_u32_e32 v4, v3, v4
	v_ashrrev_i32_e32 v4, 10, v4
	v_mul_i32_i24_e32 v5, 0x400, v4
	v_sub_u32_e32 v3, v3, v5
	v_lshrrev_b32_e32 v5, 4, v3
	v_bitop3_b32 v3, v5, v3, 32 bitop3:0x6c
	v_ashrrev_i32_e32 v5, 31, v3
	v_lshrrev_b32_e32 v5, 26, v5
	v_add_u32_e32 v5, v3, v5
	v_lshlrev_b32_e32 v7, 3, v4
	v_lshrrev_b32_e32 v6, 6, v5
	v_and_b32_e32 v7, 0xfffff0, v7
	v_and_b32_e32 v5, 0xc0, v5
	v_add_u32_e32 v6, v6, v7
	s_movk_i32 s8, 0xb00
	v_sub_u32_e32 v3, v3, v5
	v_mul_lo_u32 v6, v6, s8
	v_lshlrev_b32_e32 v4, 5, v4
	v_ashrrev_i16_sdwa v3, v205, sext(v3) dst_sel:DWORD dst_unused:UNUSED_PAD src0_sel:DWORD src1_sel:BYTE_0
	v_and_or_b32 v4, v4, 32, v6
	v_bfe_i32 v3, v3, 0, 16
	v_add_lshl_u32 v130, v4, v3, 1
	v_bfe_i32 v3, v2, 27, 1
	v_lshrrev_b32_e32 v3, 22, v3
	v_add_u32_e32 v3, v0, v3
	v_and_b32_e32 v3, 0xfffffc00, v3
	v_sub_u32_e32 v0, v0, v3
	v_lshrrev_b32_e32 v3, 4, v0
	v_ashrrev_i32_e32 v5, 31, v2
	v_bitop3_b32 v0, v3, v0, 32 bitop3:0x6c
	v_lshrrev_b32_e32 v5, 26, v5
	v_ashrrev_i32_e32 v3, 31, v0
	v_add_u32_e32 v5, v2, v5
	v_lshrrev_b32_e32 v3, 26, v3
	v_ashrrev_i32_e32 v5, 6, v5
	v_add_u32_e32 v3, v0, v3
	v_lshlrev_b32_e32 v6, 3, v5
	v_lshrrev_b32_e32 v4, 6, v3
	v_and_b32_e32 v6, 0xfffff0, v6
	s_ashr_i32 s40, s52, 6
	v_add_u32_e32 v4, v4, v6
	s_ashr_i32 s41, s52, 8
	s_lshl_b32 s53, s40, 10
	v_mul_lo_u32 v4, v4, s8
	v_readlane_b32 s8, v254, 13
	v_and_b32_e32 v3, 0xc0, v3
	s_add_u32 s4, s4, s8
	v_readlane_b32 s8, v254, 14
	v_sub_u32_e32 v0, v0, v3
	s_addc_u32 s5, s5, s8
	v_readlane_b32 s8, v254, 15
	v_lshlrev_b32_e32 v5, 5, v5
	v_ashrrev_i16_sdwa v0, v205, sext(v0) dst_sel:DWORD dst_unused:UNUSED_PAD src0_sel:DWORD src1_sel:BYTE_0
	v_readlane_b32 s9, v254, 16
	s_add_u32 s38, s4, s8
	v_and_or_b32 v4, v5, 32, v4
	v_bfe_i32 v0, v0, 0, 16
	s_addc_u32 s39, s5, s9
	s_add_i32 s4, s53, 0
	v_add_lshl_u32 v0, v4, v0, 1
	s_add_i32 m0, s4, 0x10000
	s_mov_b32 s74, s64
	global_load_lds_dwordx4 v0, s[38:39]
	s_add_i32 m0, s4, 0x12000
	s_add_u32 s8, s38, 0xb0000
	global_load_lds_dwordx4 v130, s[38:39]
	s_addc_u32 s9, s39, 0
	s_add_i32 m0, s4, 0x14000
	s_add_i32 s5, s4, 0x2000
	global_load_lds_dwordx4 v0, s[8:9]
	s_add_i32 m0, s4, 0x16000
	s_add_i32 s56, s4, 0x4000
	global_load_lds_dwordx4 v130, s[8:9]
	s_mov_b32 m0, s4
	s_add_i32 s57, s4, 0x6000
	global_load_lds_dwordx4 v0, s[82:83]
	s_mov_b32 m0, s5
	s_cmp_lg_u32 s41, 1
	global_load_lds_dwordx4 v130, s[82:83]
	s_mov_b32 m0, s56
	s_nop 0
	global_load_lds_dwordx4 v0, s[34:35]
	s_mov_b32 m0, s57
	s_nop 0
	global_load_lds_dwordx4 v130, s[34:35]
	s_cbranch_scc1 .LBB0_545
	s_barrier

.LBB0_546:
	s_add_i32 s10, s44, 0x100
	s_and_b64 s[8:9], s[42:43], exec
	s_cselect_b32 s9, 0, s10
	s_cselect_b32 s8, 0, 0
	s_add_u32 s46, s82, s9
	s_addc_u32 s47, s83, s8
	s_add_i32 s10, 0, 0x10000
	s_add_u32 s48, s38, s9
	s_addc_u32 s49, s39, s8
	s_add_i32 s8, 0, 0x14000
	s_add_u32 s54, s34, s44
	s_addc_u32 s55, s35, 0
	s_add_i32 s68, s10, s53
	s_add_i32 m0, s4, 0xc000
	s_add_i32 s9, s4, 0xe000
	s_add_i32 s65, s68, 0x2000
	s_add_u32 s50, s48, 0xb0000
	v_add_u32_e32 v148, s10, v134
	v_add_u32_e32 v164, s8, v134
	s_addc_u32 s51, s49, 0
	s_add_i32 s67, s8, s53
	ds_read_b128 v[136:139], v148
	ds_read_b128 v[140:143], v148 offset:1024
	ds_read_b128 v[144:147], v148 offset:2048
	ds_read_b128 v[148:151], v148 offset:3072
	ds_read_b128 v[152:155], v164
	ds_read_b128 v[156:159], v164 offset:1024
	ds_read_b128 v[160:163], v164 offset:2048
	ds_read_b128 v[164:167], v164 offset:3072
	s_add_i32 s66, s67, 0x2000
	s_add_i32 s64, 0, 0x18000
	s_add_i32 s63, 0, 0x1c000
	s_add_u32 s44, s46, 0xb0000
	s_addc_u32 s45, s47, 0
	s_add_i32 s62, s64, s53
	s_add_i32 s61, s62, 0x2000
	s_add_u32 s42, s48, 0xb0080
	s_addc_u32 s43, s49, 0
	s_add_i32 s72, s63, s53
	s_add_i32 s69, s72, 0x2000
	v_lshl_add_u64 v[202:203], s[54:55], 0, v[0:1]
	v_lshl_add_u64 v[202:203], v[202:203], 0, s[26:27]
	ds_read_b128 v[168:171], v135
	ds_read_b128 v[172:175], v135 offset:1024
	ds_read_b128 v[176:179], v135 offset:2048
	ds_read_b128 v[180:183], v135 offset:3072
	ds_read_b128 v[184:187], v135 offset:4096
	ds_read_b128 v[224:227], v135 offset:5120
	ds_read_b128 v[228:231], v135 offset:6144
	ds_read_b128 v[232:235], v135 offset:7168
	global_load_lds_dwordx4 v[202:203], off
	v_lshl_add_u64 v[202:203], s[54:55], 0, v[130:131]
	v_lshl_add_u64 v[202:203], v[202:203], 0, s[26:27]
	s_mov_b32 m0, s9
	s_nop 0
	global_load_lds_dwordx4 v[202:203], off
	s_waitcnt vmcnt(8)
	s_waitcnt lgkmcnt(0)
	s_barrier
	s_setprio 1
	s_waitcnt lgkmcnt(0)
	v_mfma_f32_16x16x32_bf16 v[126:129], v[136:139], v[168:171], v[126:129]
	v_mfma_f32_16x16x32_bf16 v[122:125], v[144:147], v[168:171], v[122:125]
	v_mfma_f32_16x16x32_bf16 v[118:121], v[136:139], v[176:179], v[118:121]
	v_mfma_f32_16x16x32_bf16 v[110:113], v[144:147], v[176:179], v[110:113]
	v_mfma_f32_16x16x32_bf16 v[102:105], v[136:139], v[184:187], v[102:105]
	v_mfma_f32_16x16x32_bf16 v[94:97], v[144:147], v[184:187], v[94:97]
	v_mfma_f32_16x16x32_bf16 v[86:89], v[136:139], v[228:231], v[86:89]
	v_mfma_f32_16x16x32_bf16 v[78:81], v[144:147], v[228:231], v[78:81]
	v_mfma_f32_16x16x32_bf16 v[126:129], v[140:143], v[172:175], v[126:129]
	v_mfma_f32_16x16x32_bf16 v[122:125], v[148:151], v[172:175], v[122:125]
	v_mfma_f32_16x16x32_bf16 v[118:121], v[140:143], v[180:183], v[118:121]
	v_mfma_f32_16x16x32_bf16 v[110:113], v[148:151], v[180:183], v[110:113]
	v_mfma_f32_16x16x32_bf16 v[102:105], v[140:143], v[224:227], v[102:105]
	v_mfma_f32_16x16x32_bf16 v[94:97], v[148:151], v[224:227], v[94:97]
	v_mfma_f32_16x16x32_bf16 v[86:89], v[140:143], v[232:235], v[86:89]
	v_mfma_f32_16x16x32_bf16 v[78:81], v[148:151], v[232:235], v[78:81]
	s_setprio 0
	s_setprio 1
	v_mfma_f32_16x16x32_bf16 v[114:117], v[152:155], v[168:171], v[114:117]
	v_mfma_f32_16x16x32_bf16 v[106:109], v[160:163], v[168:171], v[106:109]
	v_mfma_f32_16x16x32_bf16 v[98:101], v[152:155], v[176:179], v[98:101]
	v_mfma_f32_16x16x32_bf16 v[90:93], v[160:163], v[176:179], v[90:93]
	v_mfma_f32_16x16x32_bf16 v[82:85], v[152:155], v[184:187], v[82:85]
	v_mfma_f32_16x16x32_bf16 v[74:77], v[160:163], v[184:187], v[74:77]
	v_mfma_f32_16x16x32_bf16 v[70:73], v[152:155], v[228:231], v[70:73]
	v_mfma_f32_16x16x32_bf16 v[66:69], v[160:163], v[228:231], v[66:69]
	v_mfma_f32_16x16x32_bf16 v[114:117], v[156:159], v[172:175], v[114:117]
	v_mfma_f32_16x16x32_bf16 v[106:109], v[164:167], v[172:175], v[106:109]
	v_mfma_f32_16x16x32_bf16 v[98:101], v[156:159], v[180:183], v[98:101]
	v_mfma_f32_16x16x32_bf16 v[90:93], v[164:167], v[180:183], v[90:93]
	v_mfma_f32_16x16x32_bf16 v[82:85], v[156:159], v[224:227], v[82:85]
	v_mfma_f32_16x16x32_bf16 v[74:77], v[164:167], v[224:227], v[74:77]
	v_mfma_f32_16x16x32_bf16 v[70:73], v[156:159], v[232:235], v[70:73]
	v_mfma_f32_16x16x32_bf16 v[66:69], v[164:167], v[232:235], v[66:69]
	s_setprio 0
	s_barrier
	s_mov_b32 m0, s68
	v_lshl_add_u64 v[202:203], s[48:49], 0, v[0:1]
	ds_read_b128 v[168:171], v135 offset:16384
	ds_read_b128 v[172:175], v135 offset:17408
	ds_read_b128 v[176:179], v135 offset:18432
	ds_read_b128 v[180:183], v135 offset:19456
	ds_read_b128 v[184:187], v135 offset:20480
	ds_read_b128 v[224:227], v135 offset:21504
	ds_read_b128 v[228:231], v135 offset:22528
	ds_read_b128 v[232:235], v135 offset:23552
	global_load_lds_dwordx4 v[202:203], off
	v_lshl_add_u64 v[236:237], s[48:49], 0, v[130:131]
	s_mov_b32 m0, s65
	v_lshl_add_u64 v[238:239], s[50:51], 0, v[0:1]
	global_load_lds_dwordx4 v[236:237], off
	s_mov_b32 m0, s67
	v_lshl_add_u64 v[240:241], s[46:47], 0, v[130:131]
	global_load_lds_dwordx4 v[238:239], off
	v_lshl_add_u64 v[238:239], s[50:51], 0, v[130:131]
	s_mov_b32 m0, s66
	s_nop 0
	global_load_lds_dwordx4 v[238:239], off
	v_lshl_add_u64 v[238:239], s[46:47], 0, v[0:1]
	s_mov_b32 m0, s4
	s_nop 0
	global_load_lds_dwordx4 v[238:239], off
	s_mov_b32 m0, s5
	s_nop 0
	global_load_lds_dwordx4 v[240:241], off
	s_waitcnt vmcnt(8)
	s_waitcnt lgkmcnt(0)
	s_barrier
	s_setprio 1
	s_waitcnt lgkmcnt(0)
	v_mfma_f32_16x16x32_bf16 v[62:65], v[136:139], v[168:171], v[62:65]
	v_mfma_f32_16x16x32_bf16 v[58:61], v[144:147], v[168:171], v[58:61]
	v_mfma_f32_16x16x32_bf16 v[54:57], v[136:139], v[176:179], v[54:57]
	v_mfma_f32_16x16x32_bf16 v[46:49], v[144:147], v[176:179], v[46:49]
	v_mfma_f32_16x16x32_bf16 v[38:41], v[136:139], v[184:187], v[38:41]
	v_mfma_f32_16x16x32_bf16 v[30:33], v[144:147], v[184:187], v[30:33]
	v_mfma_f32_16x16x32_bf16 v[22:25], v[136:139], v[228:231], v[22:25]
	v_mfma_f32_16x16x32_bf16 v[14:17], v[144:147], v[228:231], v[14:17]
	v_mfma_f32_16x16x32_bf16 v[62:65], v[140:143], v[172:175], v[62:65]
	v_mfma_f32_16x16x32_bf16 v[58:61], v[148:151], v[172:175], v[58:61]
	v_mfma_f32_16x16x32_bf16 v[54:57], v[140:143], v[180:183], v[54:57]
	v_mfma_f32_16x16x32_bf16 v[46:49], v[148:151], v[180:183], v[46:49]
	v_mfma_f32_16x16x32_bf16 v[38:41], v[140:143], v[224:227], v[38:41]
	v_mfma_f32_16x16x32_bf16 v[30:33], v[148:151], v[224:227], v[30:33]
	v_mfma_f32_16x16x32_bf16 v[22:25], v[140:143], v[232:235], v[22:25]
	v_mfma_f32_16x16x32_bf16 v[14:17], v[148:151], v[232:235], v[14:17]
	s_setprio 0
	s_setprio 1
	v_mfma_f32_16x16x32_bf16 v[50:53], v[152:155], v[168:171], v[50:53]
	v_mfma_f32_16x16x32_bf16 v[42:45], v[160:163], v[168:171], v[42:45]
	v_mfma_f32_16x16x32_bf16 v[34:37], v[152:155], v[176:179], v[34:37]
	v_mfma_f32_16x16x32_bf16 v[26:29], v[160:163], v[176:179], v[26:29]
	v_mfma_f32_16x16x32_bf16 v[18:21], v[152:155], v[184:187], v[18:21]
	v_mfma_f32_16x16x32_bf16 v[10:13], v[160:163], v[184:187], v[10:13]
	v_mfma_f32_16x16x32_bf16 v[6:9], v[152:155], v[228:231], v[6:9]
	v_mfma_f32_16x16x32_bf16 v[2:5], v[160:163], v[228:231], v[2:5]
	v_mfma_f32_16x16x32_bf16 v[50:53], v[156:159], v[172:175], v[50:53]
	v_mfma_f32_16x16x32_bf16 v[42:45], v[164:167], v[172:175], v[42:45]
	v_mfma_f32_16x16x32_bf16 v[34:37], v[156:159], v[180:183], v[34:37]
	v_mfma_f32_16x16x32_bf16 v[26:29], v[164:167], v[180:183], v[26:29]
	v_mfma_f32_16x16x32_bf16 v[18:21], v[156:159], v[224:227], v[18:21]
	v_mfma_f32_16x16x32_bf16 v[10:13], v[164:167], v[224:227], v[10:13]
	v_mfma_f32_16x16x32_bf16 v[6:9], v[156:159], v[232:235], v[6:9]
	v_mfma_f32_16x16x32_bf16 v[2:5], v[164:167], v[232:235], v[2:5]
	s_setprio 0
	s_barrier
	v_add_u32_e32 v148, s64, v134
	v_add_u32_e32 v164, s63, v134
	ds_read_b128 v[136:139], v148
	ds_read_b128 v[140:143], v148 offset:1024
	ds_read_b128 v[144:147], v148 offset:2048
	ds_read_b128 v[148:151], v148 offset:3072
	ds_read_b128 v[152:155], v164
	ds_read_b128 v[156:159], v164 offset:1024
	ds_read_b128 v[160:163], v164 offset:2048
	ds_read_b128 v[164:167], v164 offset:3072
	s_mov_b32 m0, s56
	v_lshl_add_u64 v[242:243], s[44:45], 0, v[0:1]
	ds_read_b128 v[168:171], v135 offset:32768
	ds_read_b128 v[172:175], v135 offset:33792
	ds_read_b128 v[176:179], v135 offset:34816
	ds_read_b128 v[180:183], v135 offset:35840
	ds_read_b128 v[184:187], v135 offset:36864
	ds_read_b128 v[224:227], v135 offset:37888
	ds_read_b128 v[228:231], v135 offset:38912
	ds_read_b128 v[232:235], v135 offset:39936
	global_load_lds_dwordx4 v[242:243], off
	v_lshl_add_u64 v[242:243], s[44:45], 0, v[130:131]
	s_mov_b32 m0, s57
	s_nop 0
	global_load_lds_dwordx4 v[242:243], off
	s_waitcnt vmcnt(8)
	s_waitcnt lgkmcnt(0)
	s_barrier
	s_setprio 1
	s_waitcnt lgkmcnt(0)
	v_mfma_f32_16x16x32_bf16 v[126:129], v[136:139], v[168:171], v[126:129]
	v_mfma_f32_16x16x32_bf16 v[122:125], v[144:147], v[168:171], v[122:125]
	v_mfma_f32_16x16x32_bf16 v[118:121], v[136:139], v[176:179], v[118:121]
	v_mfma_f32_16x16x32_bf16 v[110:113], v[144:147], v[176:179], v[110:113]
	v_mfma_f32_16x16x32_bf16 v[102:105], v[136:139], v[184:187], v[102:105]
	v_mfma_f32_16x16x32_bf16 v[94:97], v[144:147], v[184:187], v[94:97]
	v_mfma_f32_16x16x32_bf16 v[86:89], v[136:139], v[228:231], v[86:89]
	v_mfma_f32_16x16x32_bf16 v[78:81], v[144:147], v[228:231], v[78:81]
	v_mfma_f32_16x16x32_bf16 v[126:129], v[140:143], v[172:175], v[126:129]
	v_mfma_f32_16x16x32_bf16 v[122:125], v[148:151], v[172:175], v[122:125]
	v_mfma_f32_16x16x32_bf16 v[118:121], v[140:143], v[180:183], v[118:121]
	v_mfma_f32_16x16x32_bf16 v[110:113], v[148:151], v[180:183], v[110:113]
	v_mfma_f32_16x16x32_bf16 v[102:105], v[140:143], v[224:227], v[102:105]
	v_mfma_f32_16x16x32_bf16 v[94:97], v[148:151], v[224:227], v[94:97]
	v_mfma_f32_16x16x32_bf16 v[86:89], v[140:143], v[232:235], v[86:89]
	v_mfma_f32_16x16x32_bf16 v[78:81], v[148:151], v[232:235], v[78:81]
	s_setprio 0
	s_setprio 1
	v_mfma_f32_16x16x32_bf16 v[114:117], v[152:155], v[168:171], v[114:117]
	v_mfma_f32_16x16x32_bf16 v[106:109], v[160:163], v[168:171], v[106:109]
	v_mfma_f32_16x16x32_bf16 v[98:101], v[152:155], v[176:179], v[98:101]
	v_mfma_f32_16x16x32_bf16 v[90:93], v[160:163], v[176:179], v[90:93]
	v_mfma_f32_16x16x32_bf16 v[82:85], v[152:155], v[184:187], v[82:85]
	v_mfma_f32_16x16x32_bf16 v[74:77], v[160:163], v[184:187], v[74:77]
	v_mfma_f32_16x16x32_bf16 v[70:73], v[152:155], v[228:231], v[70:73]
	v_mfma_f32_16x16x32_bf16 v[66:69], v[160:163], v[228:231], v[66:69]
	v_mfma_f32_16x16x32_bf16 v[114:117], v[156:159], v[172:175], v[114:117]
	v_mfma_f32_16x16x32_bf16 v[106:109], v[164:167], v[172:175], v[106:109]
	v_mfma_f32_16x16x32_bf16 v[98:101], v[156:159], v[180:183], v[98:101]
	v_mfma_f32_16x16x32_bf16 v[90:93], v[164:167], v[180:183], v[90:93]
	v_mfma_f32_16x16x32_bf16 v[82:85], v[156:159], v[224:227], v[82:85]
	v_mfma_f32_16x16x32_bf16 v[74:77], v[164:167], v[224:227], v[74:77]
	v_mfma_f32_16x16x32_bf16 v[70:73], v[156:159], v[232:235], v[70:73]
	v_mfma_f32_16x16x32_bf16 v[66:69], v[164:167], v[232:235], v[66:69]
	s_setprio 0
	s_barrier
	s_mov_b32 m0, s62
	v_lshl_add_u64 v[202:203], v[202:203], 0, s[26:27]
	ds_read_b128 v[168:171], v135 offset:49152
	ds_read_b128 v[172:175], v135 offset:50176
	ds_read_b128 v[176:179], v135 offset:51200
	ds_read_b128 v[180:183], v135 offset:52224
	ds_read_b128 v[184:187], v135 offset:53248
	ds_read_b128 v[224:227], v135 offset:54272
	ds_read_b128 v[228:231], v135 offset:55296
	ds_read_b128 v[232:235], v135 offset:56320
	global_load_lds_dwordx4 v[202:203], off
	v_lshl_add_u64 v[202:203], v[236:237], 0, s[26:27]
	s_mov_b32 m0, s61
	s_nop 0
	global_load_lds_dwordx4 v[202:203], off
	v_lshl_add_u64 v[202:203], s[42:43], 0, v[0:1]
	s_mov_b32 m0, s72
	s_nop 0
	global_load_lds_dwordx4 v[202:203], off
	v_lshl_add_u64 v[202:203], s[42:43], 0, v[130:131]
	s_mov_b32 m0, s69
	s_nop 0
	global_load_lds_dwordx4 v[202:203], off
	v_lshl_add_u64 v[202:203], v[238:239], 0, s[26:27]
	s_mov_b32 m0, s59
	s_nop 0
	global_load_lds_dwordx4 v[202:203], off
	v_lshl_add_u64 v[202:203], v[240:241], 0, s[26:27]
	s_mov_b32 m0, s60
	s_nop 0
	global_load_lds_dwordx4 v[202:203], off
	s_waitcnt vmcnt(8)
	s_waitcnt lgkmcnt(0)
	s_barrier
	s_setprio 1
	s_waitcnt lgkmcnt(0)
	v_mfma_f32_16x16x32_bf16 v[62:65], v[136:139], v[168:171], v[62:65]
	v_mfma_f32_16x16x32_bf16 v[58:61], v[144:147], v[168:171], v[58:61]
	v_mfma_f32_16x16x32_bf16 v[54:57], v[136:139], v[176:179], v[54:57]
	v_mfma_f32_16x16x32_bf16 v[46:49], v[144:147], v[176:179], v[46:49]
	v_mfma_f32_16x16x32_bf16 v[38:41], v[136:139], v[184:187], v[38:41]
	v_mfma_f32_16x16x32_bf16 v[30:33], v[144:147], v[184:187], v[30:33]
	v_mfma_f32_16x16x32_bf16 v[22:25], v[136:139], v[228:231], v[22:25]
	v_mfma_f32_16x16x32_bf16 v[14:17], v[144:147], v[228:231], v[14:17]
	v_mfma_f32_16x16x32_bf16 v[62:65], v[140:143], v[172:175], v[62:65]
	v_mfma_f32_16x16x32_bf16 v[58:61], v[148:151], v[172:175], v[58:61]
	v_mfma_f32_16x16x32_bf16 v[54:57], v[140:143], v[180:183], v[54:57]
	v_mfma_f32_16x16x32_bf16 v[46:49], v[148:151], v[180:183], v[46:49]
	v_mfma_f32_16x16x32_bf16 v[38:41], v[140:143], v[224:227], v[38:41]
	v_mfma_f32_16x16x32_bf16 v[30:33], v[148:151], v[224:227], v[30:33]
	v_mfma_f32_16x16x32_bf16 v[22:25], v[140:143], v[232:235], v[22:25]
	v_mfma_f32_16x16x32_bf16 v[14:17], v[148:151], v[232:235], v[14:17]
	s_setprio 0
	s_setprio 1
	v_mfma_f32_16x16x32_bf16 v[50:53], v[152:155], v[168:171], v[50:53]
	v_mfma_f32_16x16x32_bf16 v[42:45], v[160:163], v[168:171], v[42:45]
	v_mfma_f32_16x16x32_bf16 v[34:37], v[152:155], v[176:179], v[34:37]
	v_mfma_f32_16x16x32_bf16 v[26:29], v[160:163], v[176:179], v[26:29]
	v_mfma_f32_16x16x32_bf16 v[18:21], v[152:155], v[184:187], v[18:21]
	v_mfma_f32_16x16x32_bf16 v[10:13], v[160:163], v[184:187], v[10:13]
	v_mfma_f32_16x16x32_bf16 v[6:9], v[152:155], v[228:231], v[6:9]
	v_mfma_f32_16x16x32_bf16 v[2:5], v[160:163], v[228:231], v[2:5]
	v_mfma_f32_16x16x32_bf16 v[50:53], v[156:159], v[172:175], v[50:53]
	v_mfma_f32_16x16x32_bf16 v[42:45], v[164:167], v[172:175], v[42:45]
	v_mfma_f32_16x16x32_bf16 v[34:37], v[156:159], v[180:183], v[34:37]
	v_mfma_f32_16x16x32_bf16 v[26:29], v[164:167], v[180:183], v[26:29]
	v_mfma_f32_16x16x32_bf16 v[18:21], v[156:159], v[224:227], v[18:21]
	v_mfma_f32_16x16x32_bf16 v[10:13], v[164:167], v[224:227], v[10:13]
	v_mfma_f32_16x16x32_bf16 v[6:9], v[156:159], v[232:235], v[6:9]
	v_mfma_f32_16x16x32_bf16 v[2:5], v[164:167], v[232:235], v[2:5]
	s_setprio 0
	s_barrier
	s_andn2_b64 vcc, exec, s[40:41]
	s_mov_b64 s[42:43], -1
	s_mov_b64 s[40:41], 0
	s_movk_i32 s44, 0x100
	s_cbranch_vccz .LBB0_546
	v_readlane_b32 s4, v254, 17
	s_mul_i32 s5, s2, 0x5d2
	s_lshr_b32 s5, s5, 16
	v_lshl_or_b32 v0, v133, 2, s4
	v_or_b32_e32 v130, s58, v0
	v_lshlrev_b32_e32 v131, 12, v132
	v_lshl_add_u32 v130, v130, 2, v131
	v_add_u32_e32 v130, 0x8000000, v130
	s_cmp_lg_u32 s5, 0
	s_cbranch_scc1 .Lg2s_q1
	v_mov_b32_e32 v131, v130
	v_pk_mul_f32 v[126:127], v[126:127], 0.5 op_sel_hi:[1,0]
	v_pk_mul_f32 v[128:129], v[128:129], 0.5 op_sel_hi:[1,0]
	v_pk_mul_f32 v[122:123], v[122:123], 0.5 op_sel_hi:[1,0]
	v_pk_mul_f32 v[124:125], v[124:125], 0.5 op_sel_hi:[1,0]
	v_pk_mul_f32 v[114:115], v[114:115], 0.5 op_sel_hi:[1,0]
	v_pk_mul_f32 v[116:117], v[116:117], 0.5 op_sel_hi:[1,0]
	v_pk_mul_f32 v[106:107], v[106:107], 0.5 op_sel_hi:[1,0]
	v_pk_mul_f32 v[108:109], v[108:109], 0.5 op_sel_hi:[1,0]
	global_atomic_add_f32 v131, v126, s[24:25]
	global_atomic_add_f32 v131, v127, s[24:25] offset:4
	global_atomic_add_f32 v131, v128, s[24:25] offset:8
	global_atomic_add_f32 v131, v129, s[24:25] offset:12
	global_atomic_add_f32 v131, v122, s[24:25] offset:64
	global_atomic_add_f32 v131, v123, s[24:25] offset:68
	global_atomic_add_f32 v131, v124, s[24:25] offset:72
	global_atomic_add_f32 v131, v125, s[24:25] offset:76
	global_atomic_add_f32 v131, v114, s[24:25] offset:512
	global_atomic_add_f32 v131, v115, s[24:25] offset:516
	global_atomic_add_f32 v131, v116, s[24:25] offset:520
	global_atomic_add_f32 v131, v117, s[24:25] offset:524
	global_atomic_add_f32 v131, v106, s[24:25] offset:576
	global_atomic_add_f32 v131, v107, s[24:25] offset:580
	global_atomic_add_f32 v131, v108, s[24:25] offset:584
	global_atomic_add_f32 v131, v109, s[24:25] offset:588
	v_add_u32_e32 v131, 0x10000, v130
	v_pk_mul_f32 v[118:119], v[118:119], 0.5 op_sel_hi:[1,0]
	v_pk_mul_f32 v[120:121], v[120:121], 0.5 op_sel_hi:[1,0]
	v_pk_mul_f32 v[110:111], v[110:111], 0.5 op_sel_hi:[1,0]
	v_pk_mul_f32 v[112:113], v[112:113], 0.5 op_sel_hi:[1,0]
	v_pk_mul_f32 v[98:99], v[98:99], 0.5 op_sel_hi:[1,0]
	v_pk_mul_f32 v[100:101], v[100:101], 0.5 op_sel_hi:[1,0]
	v_pk_mul_f32 v[90:91], v[90:91], 0.5 op_sel_hi:[1,0]
	v_pk_mul_f32 v[92:93], v[92:93], 0.5 op_sel_hi:[1,0]
	global_atomic_add_f32 v131, v118, s[24:25]
	global_atomic_add_f32 v131, v119, s[24:25] offset:4
	global_atomic_add_f32 v131, v120, s[24:25] offset:8
	global_atomic_add_f32 v131, v121, s[24:25] offset:12
	global_atomic_add_f32 v131, v110, s[24:25] offset:64
	global_atomic_add_f32 v131, v111, s[24:25] offset:68
	global_atomic_add_f32 v131, v112, s[24:25] offset:72
	global_atomic_add_f32 v131, v113, s[24:25] offset:76
	global_atomic_add_f32 v131, v98, s[24:25] offset:512
	global_atomic_add_f32 v131, v99, s[24:25] offset:516
	global_atomic_add_f32 v131, v100, s[24:25] offset:520
	global_atomic_add_f32 v131, v101, s[24:25] offset:524
	global_atomic_add_f32 v131, v90, s[24:25] offset:576
	global_atomic_add_f32 v131, v91, s[24:25] offset:580
	global_atomic_add_f32 v131, v92, s[24:25] offset:584
	global_atomic_add_f32 v131, v93, s[24:25] offset:588
.Lg2s_q1:
	s_cmp_lg_u32 s5, 1
	s_cbranch_scc1 .Lg2s_q2
	v_add_u32_e32 v131, 0x20000, v130
	v_pk_mul_f32 v[102:103], v[102:103], 0.5 op_sel_hi:[1,0]
	v_pk_mul_f32 v[104:105], v[104:105], 0.5 op_sel_hi:[1,0]
	v_pk_mul_f32 v[94:95], v[94:95], 0.5 op_sel_hi:[1,0]
	v_pk_mul_f32 v[96:97], v[96:97], 0.5 op_sel_hi:[1,0]
	v_pk_mul_f32 v[82:83], v[82:83], 0.5 op_sel_hi:[1,0]
	v_pk_mul_f32 v[84:85], v[84:85], 0.5 op_sel_hi:[1,0]
	v_pk_mul_f32 v[74:75], v[74:75], 0.5 op_sel_hi:[1,0]
	v_pk_mul_f32 v[76:77], v[76:77], 0.5 op_sel_hi:[1,0]
	global_atomic_add_f32 v131, v102, s[24:25]
	global_atomic_add_f32 v131, v103, s[24:25] offset:4
	global_atomic_add_f32 v131, v104, s[24:25] offset:8
	global_atomic_add_f32 v131, v105, s[24:25] offset:12
	global_atomic_add_f32 v131, v94, s[24:25] offset:64
	global_atomic_add_f32 v131, v95, s[24:25] offset:68
	global_atomic_add_f32 v131, v96, s[24:25] offset:72
	global_atomic_add_f32 v131, v97, s[24:25] offset:76
	global_atomic_add_f32 v131, v82, s[24:25] offset:512
	global_atomic_add_f32 v131, v83, s[24:25] offset:516
	global_atomic_add_f32 v131, v84, s[24:25] offset:520
	global_atomic_add_f32 v131, v85, s[24:25] offset:524
	global_atomic_add_f32 v131, v74, s[24:25] offset:576
	global_atomic_add_f32 v131, v75, s[24:25] offset:580
	global_atomic_add_f32 v131, v76, s[24:25] offset:584
	global_atomic_add_f32 v131, v77, s[24:25] offset:588
	v_add_u32_e32 v131, 0x30000, v130
	v_pk_mul_f32 v[86:87], v[86:87], 0.5 op_sel_hi:[1,0]
	v_pk_mul_f32 v[88:89], v[88:89], 0.5 op_sel_hi:[1,0]
	v_pk_mul_f32 v[78:79], v[78:79], 0.5 op_sel_hi:[1,0]
	v_pk_mul_f32 v[80:81], v[80:81], 0.5 op_sel_hi:[1,0]
	v_pk_mul_f32 v[70:71], v[70:71], 0.5 op_sel_hi:[1,0]
	v_pk_mul_f32 v[72:73], v[72:73], 0.5 op_sel_hi:[1,0]
	v_pk_mul_f32 v[66:67], v[66:67], 0.5 op_sel_hi:[1,0]
	v_pk_mul_f32 v[68:69], v[68:69], 0.5 op_sel_hi:[1,0]
	global_atomic_add_f32 v131, v86, s[24:25]
	global_atomic_add_f32 v131, v87, s[24:25] offset:4
	global_atomic_add_f32 v131, v88, s[24:25] offset:8
	global_atomic_add_f32 v131, v89, s[24:25] offset:12
	global_atomic_add_f32 v131, v78, s[24:25] offset:64
	global_atomic_add_f32 v131, v79, s[24:25] offset:68
	global_atomic_add_f32 v131, v80, s[24:25] offset:72
	global_atomic_add_f32 v131, v81, s[24:25] offset:76
	global_atomic_add_f32 v131, v70, s[24:25] offset:512
	global_atomic_add_f32 v131, v71, s[24:25] offset:516
	global_atomic_add_f32 v131, v72, s[24:25] offset:520
	global_atomic_add_f32 v131, v73, s[24:25] offset:524
	global_atomic_add_f32 v131, v66, s[24:25] offset:576
	global_atomic_add_f32 v131, v67, s[24:25] offset:580
	global_atomic_add_f32 v131, v68, s[24:25] offset:584
	global_atomic_add_f32 v131, v69, s[24:25] offset:588
.Lg2s_q2:
	s_cmp_lg_u32 s5, 2
	s_cbranch_scc1 .Lg2s_q3
	v_add_u32_e32 v131, 0x80000, v130
	v_pk_mul_f32 v[62:63], v[62:63], 0.5 op_sel_hi:[1,0]
	v_pk_mul_f32 v[64:65], v[64:65], 0.5 op_sel_hi:[1,0]
	v_pk_mul_f32 v[58:59], v[58:59], 0.5 op_sel_hi:[1,0]
	v_pk_mul_f32 v[60:61], v[60:61], 0.5 op_sel_hi:[1,0]
	v_pk_mul_f32 v[50:51], v[50:51], 0.5 op_sel_hi:[1,0]
	v_pk_mul_f32 v[52:53], v[52:53], 0.5 op_sel_hi:[1,0]
	v_pk_mul_f32 v[42:43], v[42:43], 0.5 op_sel_hi:[1,0]
	v_pk_mul_f32 v[44:45], v[44:45], 0.5 op_sel_hi:[1,0]
	global_atomic_add_f32 v131, v62, s[24:25]
	global_atomic_add_f32 v131, v63, s[24:25] offset:4
	global_atomic_add_f32 v131, v64, s[24:25] offset:8
	global_atomic_add_f32 v131, v65, s[24:25] offset:12
	global_atomic_add_f32 v131, v58, s[24:25] offset:64
	global_atomic_add_f32 v131, v59, s[24:25] offset:68
	global_atomic_add_f32 v131, v60, s[24:25] offset:72
	global_atomic_add_f32 v131, v61, s[24:25] offset:76
	global_atomic_add_f32 v131, v50, s[24:25] offset:512
	global_atomic_add_f32 v131, v51, s[24:25] offset:516
	global_atomic_add_f32 v131, v52, s[24:25] offset:520
	global_atomic_add_f32 v131, v53, s[24:25] offset:524
	global_atomic_add_f32 v131, v42, s[24:25] offset:576
	global_atomic_add_f32 v131, v43, s[24:25] offset:580
	global_atomic_add_f32 v131, v44, s[24:25] offset:584
	global_atomic_add_f32 v131, v45, s[24:25] offset:588
	v_add_u32_e32 v131, 0x90000, v130
	v_pk_mul_f32 v[54:55], v[54:55], 0.5 op_sel_hi:[1,0]
	v_pk_mul_f32 v[56:57], v[56:57], 0.5 op_sel_hi:[1,0]
	v_pk_mul_f32 v[46:47], v[46:47], 0.5 op_sel_hi:[1,0]
	v_pk_mul_f32 v[48:49], v[48:49], 0.5 op_sel_hi:[1,0]
	v_pk_mul_f32 v[34:35], v[34:35], 0.5 op_sel_hi:[1,0]
	v_pk_mul_f32 v[36:37], v[36:37], 0.5 op_sel_hi:[1,0]
	v_pk_mul_f32 v[26:27], v[26:27], 0.5 op_sel_hi:[1,0]
	v_pk_mul_f32 v[28:29], v[28:29], 0.5 op_sel_hi:[1,0]
	global_atomic_add_f32 v131, v54, s[24:25]
	global_atomic_add_f32 v131, v55, s[24:25] offset:4
	global_atomic_add_f32 v131, v56, s[24:25] offset:8
	global_atomic_add_f32 v131, v57, s[24:25] offset:12
	global_atomic_add_f32 v131, v46, s[24:25] offset:64
	global_atomic_add_f32 v131, v47, s[24:25] offset:68
	global_atomic_add_f32 v131, v48, s[24:25] offset:72
	global_atomic_add_f32 v131, v49, s[24:25] offset:76
	global_atomic_add_f32 v131, v34, s[24:25] offset:512
	global_atomic_add_f32 v131, v35, s[24:25] offset:516
	global_atomic_add_f32 v131, v36, s[24:25] offset:520
	global_atomic_add_f32 v131, v37, s[24:25] offset:524
	global_atomic_add_f32 v131, v26, s[24:25] offset:576
	global_atomic_add_f32 v131, v27, s[24:25] offset:580
	global_atomic_add_f32 v131, v28, s[24:25] offset:584
	global_atomic_add_f32 v131, v29, s[24:25] offset:588
.Lg2s_q3:
	s_cmp_lg_u32 s5, 3
	s_cbranch_scc1 .Lg2s_q4
	v_add_u32_e32 v131, 0xa0000, v130
	v_pk_mul_f32 v[38:39], v[38:39], 0.5 op_sel_hi:[1,0]
	v_pk_mul_f32 v[40:41], v[40:41], 0.5 op_sel_hi:[1,0]
	v_pk_mul_f32 v[30:31], v[30:31], 0.5 op_sel_hi:[1,0]
	v_pk_mul_f32 v[32:33], v[32:33], 0.5 op_sel_hi:[1,0]
	v_pk_mul_f32 v[18:19], v[18:19], 0.5 op_sel_hi:[1,0]
	v_pk_mul_f32 v[20:21], v[20:21], 0.5 op_sel_hi:[1,0]
	v_pk_mul_f32 v[10:11], v[10:11], 0.5 op_sel_hi:[1,0]
	v_pk_mul_f32 v[12:13], v[12:13], 0.5 op_sel_hi:[1,0]
	global_atomic_add_f32 v131, v38, s[24:25]
	global_atomic_add_f32 v131, v39, s[24:25] offset:4
	global_atomic_add_f32 v131, v40, s[24:25] offset:8
	global_atomic_add_f32 v131, v41, s[24:25] offset:12
	global_atomic_add_f32 v131, v30, s[24:25] offset:64
	global_atomic_add_f32 v131, v31, s[24:25] offset:68
	global_atomic_add_f32 v131, v32, s[24:25] offset:72
	global_atomic_add_f32 v131, v33, s[24:25] offset:76
	global_atomic_add_f32 v131, v18, s[24:25] offset:512
	global_atomic_add_f32 v131, v19, s[24:25] offset:516
	global_atomic_add_f32 v131, v20, s[24:25] offset:520
	global_atomic_add_f32 v131, v21, s[24:25] offset:524
	global_atomic_add_f32 v131, v10, s[24:25] offset:576
	global_atomic_add_f32 v131, v11, s[24:25] offset:580
	global_atomic_add_f32 v131, v12, s[24:25] offset:584
	global_atomic_add_f32 v131, v13, s[24:25] offset:588
	v_add_u32_e32 v131, 0xb0000, v130
	v_pk_mul_f32 v[22:23], v[22:23], 0.5 op_sel_hi:[1,0]
	v_pk_mul_f32 v[24:25], v[24:25], 0.5 op_sel_hi:[1,0]
	v_pk_mul_f32 v[14:15], v[14:15], 0.5 op_sel_hi:[1,0]
	v_pk_mul_f32 v[16:17], v[16:17], 0.5 op_sel_hi:[1,0]
	v_pk_mul_f32 v[6:7], v[6:7], 0.5 op_sel_hi:[1,0]
	v_pk_mul_f32 v[8:9], v[8:9], 0.5 op_sel_hi:[1,0]
	v_pk_mul_f32 v[2:3], v[2:3], 0.5 op_sel_hi:[1,0]
	v_pk_mul_f32 v[4:5], v[4:5], 0.5 op_sel_hi:[1,0]
	global_atomic_add_f32 v131, v22, s[24:25]
	global_atomic_add_f32 v131, v23, s[24:25] offset:4
	global_atomic_add_f32 v131, v24, s[24:25] offset:8
	global_atomic_add_f32 v131, v25, s[24:25] offset:12
	global_atomic_add_f32 v131, v14, s[24:25] offset:64
	global_atomic_add_f32 v131, v15, s[24:25] offset:68
	global_atomic_add_f32 v131, v16, s[24:25] offset:72
	global_atomic_add_f32 v131, v17, s[24:25] offset:76
	global_atomic_add_f32 v131, v6, s[24:25] offset:512
	global_atomic_add_f32 v131, v7, s[24:25] offset:516
	global_atomic_add_f32 v131, v8, s[24:25] offset:520
	global_atomic_add_f32 v131, v9, s[24:25] offset:524
	global_atomic_add_f32 v131, v2, s[24:25] offset:576
	global_atomic_add_f32 v131, v3, s[24:25] offset:580
	global_atomic_add_f32 v131, v4, s[24:25] offset:584
	global_atomic_add_f32 v131, v5, s[24:25] offset:588
.Lg2s_q4:
	s_waitcnt vmcnt(0)
	s_cmpk_lt_u32 s52, 0x100
	s_cbranch_scc0 .LBB0_549
	s_barrier

.LBB0_1545:
	s_and_b32 s8, s2, 15
	s_and_b32 s9, s8, 3
	s_lshr_b32 s8, s8, 2
	s_lshl_b32 s8, s8, 9
	s_mov_b32 s38, 0
	v_writelane_b32 v254, s8, 15
	v_writelane_b32 v254, s38, 16
	s_lshl_b32 s39, s9, 19
	v_writelane_b32 v254, s39, 27
	v_writelane_b32 v254, s38, 28
	s_lshl_b32 s39, s9, 8
	v_writelane_b32 v254, s39, 17
	s_load_dwordx2 s[38:39], s[76:77], 0xd0
	s_waitcnt lgkmcnt(0)
	s_add_u32 s38, s38, s8
	s_addc_u32 s39, s39, 0
	s_add_u32 s8, s38, 0x9100000
	s_addc_u32 s9, s39, 0
	v_writelane_b32 v254, s8, 29
	v_writelane_b32 v254, s9, 30
	s_add_u32 s68, s38, 0x9140000
	s_addc_u32 s69, s39, 0
	s_mov_b64 s[36:37], s[68:69]
	s_cmp_lt_u32 s2, 128
	s_cselect_b64 s[8:9], -1, 0
	v_writelane_b32 v254, s8, 25
	v_writelane_b32 v254, s9, 26
	s_nop 1
	v_readlane_b32 s8, v254, 25
	v_mov_b32_e32 v2, v204
	v_readlane_b32 s9, v254, 26
	s_andn2_b64 vcc, exec, s[8:9]
	v_readfirstlane_b32 s28, v2
	s_cbranch_vccnz .LBB0_1553
	v_lshlrev_b32_e32 v0, 4, v2
	v_add_u32_e32 v3, 0x2000, v0
	v_ashrrev_i32_e32 v4, 31, v3
	v_lshrrev_b32_e32 v4, 22, v4
	v_add_u32_e32 v4, v3, v4
	v_ashrrev_i32_e32 v4, 10, v4
	v_mul_i32_i24_e32 v5, 0x400, v4
	v_sub_u32_e32 v3, v3, v5
	v_lshrrev_b32_e32 v5, 4, v3
	v_bitop3_b32 v3, v5, v3, 32 bitop3:0x6c
	v_ashrrev_i32_e32 v5, 31, v3
	v_lshrrev_b32_e32 v5, 26, v5
	v_add_u32_e32 v5, v3, v5
	v_lshrrev_b32_e32 v6, 6, v5
	v_lshlrev_b32_e32 v7, 3, v4
	v_and_b32_e32 v5, 0xc0, v5
	v_and_b32_e32 v7, 0x1ffff0, v7
	v_lshlrev_b32_e32 v4, 5, v4
	v_sub_u32_e32 v3, v3, v5
	v_add_u32_e32 v6, v6, v7
	v_and_b32_e32 v4, 32, v4
	v_ashrrev_i16_sdwa v3, v205, sext(v3) dst_sel:DWORD dst_unused:UNUSED_PAD src0_sel:DWORD src1_sel:BYTE_0
	v_lshl_or_b32 v4, v6, 10, v4
	v_bfe_i32 v3, v3, 0, 16
	v_add_lshl_u32 v130, v4, v3, 1
	v_bfe_i32 v3, v2, 27, 1
	v_lshrrev_b32_e32 v3, 22, v3
	v_add_u32_e32 v3, v0, v3
	v_and_b32_e32 v3, 0xfffffc00, v3
	v_sub_u32_e32 v0, v0, v3
	v_lshrrev_b32_e32 v3, 4, v0
	v_bitop3_b32 v0, v3, v0, 32 bitop3:0x6c
	v_ashrrev_i32_e32 v5, 31, v2
	v_ashrrev_i32_e32 v3, 31, v0
	v_lshrrev_b32_e32 v5, 26, v5
	s_ashr_i32 s40, s28, 6
	v_lshrrev_b32_e32 v3, 26, v3
	v_add_u32_e32 v5, v2, v5
	s_ashr_i32 s41, s28, 8
	s_lshl_b32 s54, s40, 10
	v_add_u32_e32 v3, v0, v3
	v_ashrrev_i32_e32 v5, 6, v5
	v_readlane_b32 s8, v254, 27
	v_lshrrev_b32_e32 v4, 6, v3
	v_lshlrev_b32_e32 v6, 3, v5
	v_and_b32_e32 v3, 0xc0, v3
	v_readlane_b32 s9, v254, 28
	s_add_u32 s4, s4, s8
	v_and_b32_e32 v6, 0x1ffff0, v6
	v_lshlrev_b32_e32 v5, 5, v5
	v_sub_u32_e32 v0, v0, v3
	s_addc_u32 s5, s5, s9
	v_readlane_b32 s8, v254, 15
	v_add_u32_e32 v4, v4, v6
	v_and_b32_e32 v5, 32, v5
	v_ashrrev_i16_sdwa v0, v205, sext(v0) dst_sel:DWORD dst_unused:UNUSED_PAD src0_sel:DWORD src1_sel:BYTE_0
	v_readlane_b32 s9, v254, 16
	s_add_u32 s38, s4, s8
	v_lshl_or_b32 v4, v4, 10, v5
	v_bfe_i32 v0, v0, 0, 16
	s_addc_u32 s39, s5, s9
	s_add_i32 s4, s54, 0
	v_add_lshl_u32 v0, v4, v0, 1
	s_add_i32 m0, s4, 0x10000
	v_readlane_b32 s72, v254, 29
	global_load_lds_dwordx4 v0, s[38:39]
	s_add_i32 m0, s4, 0x12000
	s_add_u32 s8, s38, 0x40000
	global_load_lds_dwordx4 v130, s[38:39]
	s_addc_u32 s9, s39, 0
	s_add_i32 m0, s4, 0x14000
	v_readlane_b32 s73, v254, 30
	global_load_lds_dwordx4 v0, s[8:9]
	s_add_i32 m0, s4, 0x16000
	s_add_i32 s5, s4, 0x2000
	global_load_lds_dwordx4 v130, s[8:9]
	s_mov_b32 m0, s4
	s_add_i32 s55, s4, 0x4000
	global_load_lds_dwordx4 v0, s[72:73]
	s_mov_b32 m0, s5
	s_add_i32 s56, s4, 0x6000
	global_load_lds_dwordx4 v130, s[72:73]
	s_mov_b32 m0, s55
	s_cmp_lg_u32 s41, 1
	global_load_lds_dwordx4 v0, s[68:69]
	s_mov_b32 m0, s56
	s_nop 0
	global_load_lds_dwordx4 v130, s[68:69]
	s_cbranch_scc1 .LBB0_1548
	s_barrier

.LBB0_1549:
	s_add_i32 s10, s44, 0x100
	s_and_b64 s[8:9], s[42:43], exec
	s_cselect_b32 s9, 0, s10
	s_cselect_b32 s8, 0, 0
	s_add_u32 s46, s72, s9
	s_addc_u32 s47, s73, s8
	s_add_i32 s10, 0, 0x10000
	s_add_u32 s48, s38, s9
	s_addc_u32 s49, s39, s8
	s_add_i32 s8, 0, 0x14000
	s_add_u32 s52, s68, s44
	s_addc_u32 s53, s69, 0
	s_add_i32 s67, s10, s54
	s_add_i32 m0, s4, 0xc000
	s_add_i32 s9, s4, 0xe000
	s_add_i32 s64, s67, 0x2000
	s_add_u32 s50, s48, 0x40000
	s_addc_u32 s51, s49, 0
	s_add_i32 s66, s8, s54
	v_add_u32_e32 v148, s10, v134
	v_add_u32_e32 v164, s8, v134
	s_add_i32 s65, s66, 0x2000
	s_add_i32 s63, 0, 0x18000
	s_add_i32 s62, 0, 0x1c000
	ds_read_b128 v[136:139], v148
	ds_read_b128 v[140:143], v148 offset:1024
	ds_read_b128 v[144:147], v148 offset:2048
	ds_read_b128 v[148:151], v148 offset:3072
	ds_read_b128 v[152:155], v164
	ds_read_b128 v[156:159], v164 offset:1024
	ds_read_b128 v[160:163], v164 offset:2048
	ds_read_b128 v[164:167], v164 offset:3072
	s_add_u32 s44, s46, 0x40000
	s_addc_u32 s45, s47, 0
	s_add_i32 s61, s63, s54
	s_add_i32 s60, s61, 0x2000
	s_add_u32 s42, s48, 0x40080
	s_addc_u32 s43, s49, 0
	s_add_i32 s69, s62, s54
	s_add_i32 s68, s69, 0x2000
	v_lshl_add_u64 v[202:203], s[52:53], 0, v[0:1]
	v_lshl_add_u64 v[202:203], v[202:203], 0, s[26:27]
	ds_read_b128 v[168:171], v135
	ds_read_b128 v[172:175], v135 offset:1024
	ds_read_b128 v[176:179], v135 offset:2048
	ds_read_b128 v[180:183], v135 offset:3072
	ds_read_b128 v[184:187], v135 offset:4096
	ds_read_b128 v[224:227], v135 offset:5120
	ds_read_b128 v[228:231], v135 offset:6144
	ds_read_b128 v[232:235], v135 offset:7168
	global_load_lds_dwordx4 v[202:203], off
	v_lshl_add_u64 v[202:203], s[52:53], 0, v[130:131]
	v_lshl_add_u64 v[202:203], v[202:203], 0, s[26:27]
	s_mov_b32 m0, s9
	s_nop 0
	global_load_lds_dwordx4 v[202:203], off
	s_waitcnt vmcnt(8)
	s_waitcnt lgkmcnt(0)
	s_barrier
	s_setprio 1
	s_waitcnt lgkmcnt(0)
	v_mfma_f32_16x16x32_bf16 v[126:129], v[136:139], v[168:171], v[126:129]
	v_mfma_f32_16x16x32_bf16 v[122:125], v[144:147], v[168:171], v[122:125]
	v_mfma_f32_16x16x32_bf16 v[118:121], v[136:139], v[176:179], v[118:121]
	v_mfma_f32_16x16x32_bf16 v[114:117], v[144:147], v[176:179], v[114:117]
	v_mfma_f32_16x16x32_bf16 v[102:105], v[136:139], v[184:187], v[102:105]
	v_mfma_f32_16x16x32_bf16 v[98:101], v[144:147], v[184:187], v[98:101]
	v_mfma_f32_16x16x32_bf16 v[86:89], v[136:139], v[228:231], v[86:89]
	v_mfma_f32_16x16x32_bf16 v[82:85], v[144:147], v[228:231], v[82:85]
	v_mfma_f32_16x16x32_bf16 v[126:129], v[140:143], v[172:175], v[126:129]
	v_mfma_f32_16x16x32_bf16 v[122:125], v[148:151], v[172:175], v[122:125]
	v_mfma_f32_16x16x32_bf16 v[118:121], v[140:143], v[180:183], v[118:121]
	v_mfma_f32_16x16x32_bf16 v[114:117], v[148:151], v[180:183], v[114:117]
	v_mfma_f32_16x16x32_bf16 v[102:105], v[140:143], v[224:227], v[102:105]
	v_mfma_f32_16x16x32_bf16 v[98:101], v[148:151], v[224:227], v[98:101]
	v_mfma_f32_16x16x32_bf16 v[86:89], v[140:143], v[232:235], v[86:89]
	v_mfma_f32_16x16x32_bf16 v[82:85], v[148:151], v[232:235], v[82:85]
	s_setprio 0
	s_setprio 1
	v_mfma_f32_16x16x32_bf16 v[110:113], v[152:155], v[168:171], v[110:113]
	v_mfma_f32_16x16x32_bf16 v[106:109], v[160:163], v[168:171], v[106:109]
	v_mfma_f32_16x16x32_bf16 v[94:97], v[152:155], v[176:179], v[94:97]
	v_mfma_f32_16x16x32_bf16 v[90:93], v[160:163], v[176:179], v[90:93]
	v_mfma_f32_16x16x32_bf16 v[78:81], v[152:155], v[184:187], v[78:81]
	v_mfma_f32_16x16x32_bf16 v[74:77], v[160:163], v[184:187], v[74:77]
	v_mfma_f32_16x16x32_bf16 v[70:73], v[152:155], v[228:231], v[70:73]
	v_mfma_f32_16x16x32_bf16 v[66:69], v[160:163], v[228:231], v[66:69]
	v_mfma_f32_16x16x32_bf16 v[110:113], v[156:159], v[172:175], v[110:113]
	v_mfma_f32_16x16x32_bf16 v[106:109], v[164:167], v[172:175], v[106:109]
	v_mfma_f32_16x16x32_bf16 v[94:97], v[156:159], v[180:183], v[94:97]
	v_mfma_f32_16x16x32_bf16 v[90:93], v[164:167], v[180:183], v[90:93]
	v_mfma_f32_16x16x32_bf16 v[78:81], v[156:159], v[224:227], v[78:81]
	v_mfma_f32_16x16x32_bf16 v[74:77], v[164:167], v[224:227], v[74:77]
	v_mfma_f32_16x16x32_bf16 v[70:73], v[156:159], v[232:235], v[70:73]
	v_mfma_f32_16x16x32_bf16 v[66:69], v[164:167], v[232:235], v[66:69]
	s_setprio 0
	s_barrier
	s_mov_b32 m0, s67
	v_lshl_add_u64 v[202:203], s[48:49], 0, v[0:1]
	ds_read_b128 v[168:171], v135 offset:16384
	ds_read_b128 v[172:175], v135 offset:17408
	ds_read_b128 v[176:179], v135 offset:18432
	ds_read_b128 v[180:183], v135 offset:19456
	ds_read_b128 v[184:187], v135 offset:20480
	ds_read_b128 v[224:227], v135 offset:21504
	ds_read_b128 v[228:231], v135 offset:22528
	ds_read_b128 v[232:235], v135 offset:23552
	global_load_lds_dwordx4 v[202:203], off
	v_lshl_add_u64 v[208:209], s[48:49], 0, v[130:131]
	s_mov_b32 m0, s64
	v_lshl_add_u64 v[236:237], s[50:51], 0, v[0:1]
	global_load_lds_dwordx4 v[208:209], off
	s_mov_b32 m0, s66
	v_lshl_add_u64 v[238:239], s[46:47], 0, v[130:131]
	global_load_lds_dwordx4 v[236:237], off
	v_lshl_add_u64 v[236:237], s[50:51], 0, v[130:131]
	s_mov_b32 m0, s65
	s_nop 0
	global_load_lds_dwordx4 v[236:237], off
	v_lshl_add_u64 v[236:237], s[46:47], 0, v[0:1]
	s_mov_b32 m0, s4
	s_nop 0
	global_load_lds_dwordx4 v[236:237], off
	s_mov_b32 m0, s5
	s_nop 0
	global_load_lds_dwordx4 v[238:239], off
	s_waitcnt vmcnt(8)
	s_waitcnt lgkmcnt(0)
	s_barrier
	s_setprio 1
	s_waitcnt lgkmcnt(0)
	v_mfma_f32_16x16x32_bf16 v[62:65], v[136:139], v[168:171], v[62:65]
	v_mfma_f32_16x16x32_bf16 v[58:61], v[144:147], v[168:171], v[58:61]
	v_mfma_f32_16x16x32_bf16 v[54:57], v[136:139], v[176:179], v[54:57]
	v_mfma_f32_16x16x32_bf16 v[50:53], v[144:147], v[176:179], v[50:53]
	v_mfma_f32_16x16x32_bf16 v[38:41], v[136:139], v[184:187], v[38:41]
	v_mfma_f32_16x16x32_bf16 v[34:37], v[144:147], v[184:187], v[34:37]
	v_mfma_f32_16x16x32_bf16 v[22:25], v[136:139], v[228:231], v[22:25]
	v_mfma_f32_16x16x32_bf16 v[18:21], v[144:147], v[228:231], v[18:21]
	v_mfma_f32_16x16x32_bf16 v[62:65], v[140:143], v[172:175], v[62:65]
	v_mfma_f32_16x16x32_bf16 v[58:61], v[148:151], v[172:175], v[58:61]
	v_mfma_f32_16x16x32_bf16 v[54:57], v[140:143], v[180:183], v[54:57]
	v_mfma_f32_16x16x32_bf16 v[50:53], v[148:151], v[180:183], v[50:53]
	v_mfma_f32_16x16x32_bf16 v[38:41], v[140:143], v[224:227], v[38:41]
	v_mfma_f32_16x16x32_bf16 v[34:37], v[148:151], v[224:227], v[34:37]
	v_mfma_f32_16x16x32_bf16 v[22:25], v[140:143], v[232:235], v[22:25]
	v_mfma_f32_16x16x32_bf16 v[18:21], v[148:151], v[232:235], v[18:21]
	s_setprio 0
	s_setprio 1
	v_mfma_f32_16x16x32_bf16 v[46:49], v[152:155], v[168:171], v[46:49]
	v_mfma_f32_16x16x32_bf16 v[42:45], v[160:163], v[168:171], v[42:45]
	v_mfma_f32_16x16x32_bf16 v[30:33], v[152:155], v[176:179], v[30:33]
	v_mfma_f32_16x16x32_bf16 v[26:29], v[160:163], v[176:179], v[26:29]
	v_mfma_f32_16x16x32_bf16 v[14:17], v[152:155], v[184:187], v[14:17]
	v_mfma_f32_16x16x32_bf16 v[10:13], v[160:163], v[184:187], v[10:13]
	v_mfma_f32_16x16x32_bf16 v[6:9], v[152:155], v[228:231], v[6:9]
	v_mfma_f32_16x16x32_bf16 v[2:5], v[160:163], v[228:231], v[2:5]
	v_mfma_f32_16x16x32_bf16 v[46:49], v[156:159], v[172:175], v[46:49]
	v_mfma_f32_16x16x32_bf16 v[42:45], v[164:167], v[172:175], v[42:45]
	v_mfma_f32_16x16x32_bf16 v[30:33], v[156:159], v[180:183], v[30:33]
	v_mfma_f32_16x16x32_bf16 v[26:29], v[164:167], v[180:183], v[26:29]
	v_mfma_f32_16x16x32_bf16 v[14:17], v[156:159], v[224:227], v[14:17]
	v_mfma_f32_16x16x32_bf16 v[10:13], v[164:167], v[224:227], v[10:13]
	v_mfma_f32_16x16x32_bf16 v[6:9], v[156:159], v[232:235], v[6:9]
	v_mfma_f32_16x16x32_bf16 v[2:5], v[164:167], v[232:235], v[2:5]
	s_setprio 0
	s_barrier
	v_add_u32_e32 v148, s63, v134
	v_add_u32_e32 v164, s62, v134
	ds_read_b128 v[136:139], v148
	ds_read_b128 v[140:143], v148 offset:1024
	ds_read_b128 v[144:147], v148 offset:2048
	ds_read_b128 v[148:151], v148 offset:3072
	ds_read_b128 v[152:155], v164
	ds_read_b128 v[156:159], v164 offset:1024
	ds_read_b128 v[160:163], v164 offset:2048
	ds_read_b128 v[164:167], v164 offset:3072
	s_mov_b32 m0, s55
	v_lshl_add_u64 v[240:241], s[44:45], 0, v[0:1]
	ds_read_b128 v[168:171], v135 offset:32768
	ds_read_b128 v[172:175], v135 offset:33792
	ds_read_b128 v[176:179], v135 offset:34816
	ds_read_b128 v[180:183], v135 offset:35840
	ds_read_b128 v[184:187], v135 offset:36864
	ds_read_b128 v[224:227], v135 offset:37888
	ds_read_b128 v[228:231], v135 offset:38912
	ds_read_b128 v[232:235], v135 offset:39936
	global_load_lds_dwordx4 v[240:241], off
	v_lshl_add_u64 v[240:241], s[44:45], 0, v[130:131]
	s_mov_b32 m0, s56
	s_nop 0
	global_load_lds_dwordx4 v[240:241], off
	s_waitcnt vmcnt(8)
	s_waitcnt lgkmcnt(0)
	s_barrier
	s_setprio 1
	s_waitcnt lgkmcnt(0)
	v_mfma_f32_16x16x32_bf16 v[126:129], v[136:139], v[168:171], v[126:129]
	v_mfma_f32_16x16x32_bf16 v[122:125], v[144:147], v[168:171], v[122:125]
	v_mfma_f32_16x16x32_bf16 v[118:121], v[136:139], v[176:179], v[118:121]
	v_mfma_f32_16x16x32_bf16 v[114:117], v[144:147], v[176:179], v[114:117]
	v_mfma_f32_16x16x32_bf16 v[102:105], v[136:139], v[184:187], v[102:105]
	v_mfma_f32_16x16x32_bf16 v[98:101], v[144:147], v[184:187], v[98:101]
	v_mfma_f32_16x16x32_bf16 v[86:89], v[136:139], v[228:231], v[86:89]
	v_mfma_f32_16x16x32_bf16 v[82:85], v[144:147], v[228:231], v[82:85]
	v_mfma_f32_16x16x32_bf16 v[126:129], v[140:143], v[172:175], v[126:129]
	v_mfma_f32_16x16x32_bf16 v[122:125], v[148:151], v[172:175], v[122:125]
	v_mfma_f32_16x16x32_bf16 v[118:121], v[140:143], v[180:183], v[118:121]
	v_mfma_f32_16x16x32_bf16 v[114:117], v[148:151], v[180:183], v[114:117]
	v_mfma_f32_16x16x32_bf16 v[102:105], v[140:143], v[224:227], v[102:105]
	v_mfma_f32_16x16x32_bf16 v[98:101], v[148:151], v[224:227], v[98:101]
	v_mfma_f32_16x16x32_bf16 v[86:89], v[140:143], v[232:235], v[86:89]
	v_mfma_f32_16x16x32_bf16 v[82:85], v[148:151], v[232:235], v[82:85]
	s_setprio 0
	s_setprio 1
	v_mfma_f32_16x16x32_bf16 v[110:113], v[152:155], v[168:171], v[110:113]
	v_mfma_f32_16x16x32_bf16 v[106:109], v[160:163], v[168:171], v[106:109]
	v_mfma_f32_16x16x32_bf16 v[94:97], v[152:155], v[176:179], v[94:97]
	v_mfma_f32_16x16x32_bf16 v[90:93], v[160:163], v[176:179], v[90:93]
	v_mfma_f32_16x16x32_bf16 v[78:81], v[152:155], v[184:187], v[78:81]
	v_mfma_f32_16x16x32_bf16 v[74:77], v[160:163], v[184:187], v[74:77]
	v_mfma_f32_16x16x32_bf16 v[70:73], v[152:155], v[228:231], v[70:73]
	v_mfma_f32_16x16x32_bf16 v[66:69], v[160:163], v[228:231], v[66:69]
	v_mfma_f32_16x16x32_bf16 v[110:113], v[156:159], v[172:175], v[110:113]
	v_mfma_f32_16x16x32_bf16 v[106:109], v[164:167], v[172:175], v[106:109]
	v_mfma_f32_16x16x32_bf16 v[94:97], v[156:159], v[180:183], v[94:97]
	v_mfma_f32_16x16x32_bf16 v[90:93], v[164:167], v[180:183], v[90:93]
	v_mfma_f32_16x16x32_bf16 v[78:81], v[156:159], v[224:227], v[78:81]
	v_mfma_f32_16x16x32_bf16 v[74:77], v[164:167], v[224:227], v[74:77]
	v_mfma_f32_16x16x32_bf16 v[70:73], v[156:159], v[232:235], v[70:73]
	v_mfma_f32_16x16x32_bf16 v[66:69], v[164:167], v[232:235], v[66:69]
	s_setprio 0
	s_barrier
	s_mov_b32 m0, s61
	v_lshl_add_u64 v[202:203], v[202:203], 0, s[26:27]
	ds_read_b128 v[168:171], v135 offset:49152
	ds_read_b128 v[172:175], v135 offset:50176
	ds_read_b128 v[176:179], v135 offset:51200
	ds_read_b128 v[180:183], v135 offset:52224
	ds_read_b128 v[184:187], v135 offset:53248
	ds_read_b128 v[224:227], v135 offset:54272
	ds_read_b128 v[228:231], v135 offset:55296
	ds_read_b128 v[232:235], v135 offset:56320
	global_load_lds_dwordx4 v[202:203], off
	v_lshl_add_u64 v[202:203], v[208:209], 0, s[26:27]
	s_mov_b32 m0, s60
	s_nop 0
	global_load_lds_dwordx4 v[202:203], off
	v_lshl_add_u64 v[202:203], s[42:43], 0, v[0:1]
	s_mov_b32 m0, s69
	s_nop 0
	global_load_lds_dwordx4 v[202:203], off
	v_lshl_add_u64 v[202:203], s[42:43], 0, v[130:131]
	s_mov_b32 m0, s68
	s_mov_b64 s[68:69], s[36:37]
	global_load_lds_dwordx4 v[202:203], off
	v_lshl_add_u64 v[202:203], v[236:237], 0, s[26:27]
	s_mov_b32 m0, s58
	s_nop 0
	global_load_lds_dwordx4 v[202:203], off
	v_lshl_add_u64 v[202:203], v[238:239], 0, s[26:27]
	s_mov_b32 m0, s59
	s_nop 0
	global_load_lds_dwordx4 v[202:203], off
	s_waitcnt vmcnt(8)
	s_waitcnt lgkmcnt(0)
	s_barrier
	s_setprio 1
	s_waitcnt lgkmcnt(0)
	v_mfma_f32_16x16x32_bf16 v[62:65], v[136:139], v[168:171], v[62:65]
	v_mfma_f32_16x16x32_bf16 v[58:61], v[144:147], v[168:171], v[58:61]
	v_mfma_f32_16x16x32_bf16 v[54:57], v[136:139], v[176:179], v[54:57]
	v_mfma_f32_16x16x32_bf16 v[50:53], v[144:147], v[176:179], v[50:53]
	v_mfma_f32_16x16x32_bf16 v[38:41], v[136:139], v[184:187], v[38:41]
	v_mfma_f32_16x16x32_bf16 v[34:37], v[144:147], v[184:187], v[34:37]
	v_mfma_f32_16x16x32_bf16 v[22:25], v[136:139], v[228:231], v[22:25]
	v_mfma_f32_16x16x32_bf16 v[18:21], v[144:147], v[228:231], v[18:21]
	v_mfma_f32_16x16x32_bf16 v[62:65], v[140:143], v[172:175], v[62:65]
	v_mfma_f32_16x16x32_bf16 v[58:61], v[148:151], v[172:175], v[58:61]
	v_mfma_f32_16x16x32_bf16 v[54:57], v[140:143], v[180:183], v[54:57]
	v_mfma_f32_16x16x32_bf16 v[50:53], v[148:151], v[180:183], v[50:53]
	v_mfma_f32_16x16x32_bf16 v[38:41], v[140:143], v[224:227], v[38:41]
	v_mfma_f32_16x16x32_bf16 v[34:37], v[148:151], v[224:227], v[34:37]
	v_mfma_f32_16x16x32_bf16 v[22:25], v[140:143], v[232:235], v[22:25]
	v_mfma_f32_16x16x32_bf16 v[18:21], v[148:151], v[232:235], v[18:21]
	s_setprio 0
	s_setprio 1
	v_mfma_f32_16x16x32_bf16 v[46:49], v[152:155], v[168:171], v[46:49]
	v_mfma_f32_16x16x32_bf16 v[42:45], v[160:163], v[168:171], v[42:45]
	v_mfma_f32_16x16x32_bf16 v[30:33], v[152:155], v[176:179], v[30:33]
	v_mfma_f32_16x16x32_bf16 v[26:29], v[160:163], v[176:179], v[26:29]
	v_mfma_f32_16x16x32_bf16 v[14:17], v[152:155], v[184:187], v[14:17]
	v_mfma_f32_16x16x32_bf16 v[10:13], v[160:163], v[184:187], v[10:13]
	v_mfma_f32_16x16x32_bf16 v[6:9], v[152:155], v[228:231], v[6:9]
	v_mfma_f32_16x16x32_bf16 v[2:5], v[160:163], v[228:231], v[2:5]
	v_mfma_f32_16x16x32_bf16 v[46:49], v[156:159], v[172:175], v[46:49]
	v_mfma_f32_16x16x32_bf16 v[42:45], v[164:167], v[172:175], v[42:45]
	v_mfma_f32_16x16x32_bf16 v[30:33], v[156:159], v[180:183], v[30:33]
	v_mfma_f32_16x16x32_bf16 v[26:29], v[164:167], v[180:183], v[26:29]
	v_mfma_f32_16x16x32_bf16 v[14:17], v[156:159], v[224:227], v[14:17]
	v_mfma_f32_16x16x32_bf16 v[10:13], v[164:167], v[224:227], v[10:13]
	v_mfma_f32_16x16x32_bf16 v[6:9], v[156:159], v[232:235], v[6:9]
	v_mfma_f32_16x16x32_bf16 v[2:5], v[164:167], v[232:235], v[2:5]
	s_setprio 0
	s_barrier
	s_andn2_b64 vcc, exec, s[40:41]
	s_mov_b64 s[42:43], -1
	s_mov_b64 s[40:41], 0
	s_movk_i32 s44, 0x100
	s_cbranch_vccz .LBB0_1549
	v_readlane_b32 s4, v254, 17
	s_lshr_b32 s5, s2, 4
	v_lshl_or_b32 v0, v133, 2, s4
	v_or_b32_e32 v130, s57, v0
	v_lshlrev_b32_e32 v131, 12, v132
	v_lshl_add_u32 v130, v130, 2, v131
	v_add_u32_e32 v130, 0x8000000, v130
	s_cmp_lg_u32 s5, 0
	s_cbranch_scc1 .Lg4s_q1
	v_mov_b32_e32 v131, v130
	global_atomic_add_f32 v131, v126, s[24:25]
	global_atomic_add_f32 v131, v127, s[24:25] offset:4
	global_atomic_add_f32 v131, v128, s[24:25] offset:8
	global_atomic_add_f32 v131, v129, s[24:25] offset:12
	global_atomic_add_f32 v131, v122, s[24:25] offset:64
	global_atomic_add_f32 v131, v123, s[24:25] offset:68
	global_atomic_add_f32 v131, v124, s[24:25] offset:72
	global_atomic_add_f32 v131, v125, s[24:25] offset:76
	global_atomic_add_f32 v131, v110, s[24:25] offset:512
	global_atomic_add_f32 v131, v111, s[24:25] offset:516
	global_atomic_add_f32 v131, v112, s[24:25] offset:520
	global_atomic_add_f32 v131, v113, s[24:25] offset:524
	global_atomic_add_f32 v131, v106, s[24:25] offset:576
	global_atomic_add_f32 v131, v107, s[24:25] offset:580
	global_atomic_add_f32 v131, v108, s[24:25] offset:584
	global_atomic_add_f32 v131, v109, s[24:25] offset:588
.Lg4s_q1:
	s_cmp_lg_u32 s5, 1
	s_cbranch_scc1 .Lg4s_q2
	v_add_u32_e32 v131, 0x10000, v130
	global_atomic_add_f32 v131, v118, s[24:25]
	global_atomic_add_f32 v131, v119, s[24:25] offset:4
	global_atomic_add_f32 v131, v120, s[24:25] offset:8
	global_atomic_add_f32 v131, v121, s[24:25] offset:12
	global_atomic_add_f32 v131, v114, s[24:25] offset:64
	global_atomic_add_f32 v131, v115, s[24:25] offset:68
	global_atomic_add_f32 v131, v116, s[24:25] offset:72
	global_atomic_add_f32 v131, v117, s[24:25] offset:76
	global_atomic_add_f32 v131, v94, s[24:25] offset:512
	global_atomic_add_f32 v131, v95, s[24:25] offset:516
	global_atomic_add_f32 v131, v96, s[24:25] offset:520
	global_atomic_add_f32 v131, v97, s[24:25] offset:524
	global_atomic_add_f32 v131, v90, s[24:25] offset:576
	global_atomic_add_f32 v131, v91, s[24:25] offset:580
	global_atomic_add_f32 v131, v92, s[24:25] offset:584
	global_atomic_add_f32 v131, v93, s[24:25] offset:588
.Lg4s_q2:
	s_cmp_lg_u32 s5, 2
	s_cbranch_scc1 .Lg4s_q3
	v_add_u32_e32 v131, 0x20000, v130
	global_atomic_add_f32 v131, v102, s[24:25]
	global_atomic_add_f32 v131, v103, s[24:25] offset:4
	global_atomic_add_f32 v131, v104, s[24:25] offset:8
	global_atomic_add_f32 v131, v105, s[24:25] offset:12
	global_atomic_add_f32 v131, v98, s[24:25] offset:64
	global_atomic_add_f32 v131, v99, s[24:25] offset:68
	global_atomic_add_f32 v131, v100, s[24:25] offset:72
	global_atomic_add_f32 v131, v101, s[24:25] offset:76
	global_atomic_add_f32 v131, v78, s[24:25] offset:512
	global_atomic_add_f32 v131, v79, s[24:25] offset:516
	global_atomic_add_f32 v131, v80, s[24:25] offset:520
	global_atomic_add_f32 v131, v81, s[24:25] offset:524
	global_atomic_add_f32 v131, v74, s[24:25] offset:576
	global_atomic_add_f32 v131, v75, s[24:25] offset:580
	global_atomic_add_f32 v131, v76, s[24:25] offset:584
	global_atomic_add_f32 v131, v77, s[24:25] offset:588
.Lg4s_q3:
	s_cmp_lg_u32 s5, 3
	s_cbranch_scc1 .Lg4s_q4
	v_add_u32_e32 v131, 0x30000, v130
	global_atomic_add_f32 v131, v86, s[24:25]
	global_atomic_add_f32 v131, v87, s[24:25] offset:4
	global_atomic_add_f32 v131, v88, s[24:25] offset:8
	global_atomic_add_f32 v131, v89, s[24:25] offset:12
	global_atomic_add_f32 v131, v82, s[24:25] offset:64
	global_atomic_add_f32 v131, v83, s[24:25] offset:68
	global_atomic_add_f32 v131, v84, s[24:25] offset:72
	global_atomic_add_f32 v131, v85, s[24:25] offset:76
	global_atomic_add_f32 v131, v70, s[24:25] offset:512
	global_atomic_add_f32 v131, v71, s[24:25] offset:516
	global_atomic_add_f32 v131, v72, s[24:25] offset:520
	global_atomic_add_f32 v131, v73, s[24:25] offset:524
	global_atomic_add_f32 v131, v66, s[24:25] offset:576
	global_atomic_add_f32 v131, v67, s[24:25] offset:580
	global_atomic_add_f32 v131, v68, s[24:25] offset:584
	global_atomic_add_f32 v131, v69, s[24:25] offset:588
.Lg4s_q4:
	s_cmp_lg_u32 s5, 4
	s_cbranch_scc1 .Lg4s_q5
	v_add_u32_e32 v131, 0x80000, v130
	global_atomic_add_f32 v131, v62, s[24:25]
	global_atomic_add_f32 v131, v63, s[24:25] offset:4
	global_atomic_add_f32 v131, v64, s[24:25] offset:8
	global_atomic_add_f32 v131, v65, s[24:25] offset:12
	global_atomic_add_f32 v131, v58, s[24:25] offset:64
	global_atomic_add_f32 v131, v59, s[24:25] offset:68
	global_atomic_add_f32 v131, v60, s[24:25] offset:72
	global_atomic_add_f32 v131, v61, s[24:25] offset:76
	global_atomic_add_f32 v131, v46, s[24:25] offset:512
	global_atomic_add_f32 v131, v47, s[24:25] offset:516
	global_atomic_add_f32 v131, v48, s[24:25] offset:520
	global_atomic_add_f32 v131, v49, s[24:25] offset:524
	global_atomic_add_f32 v131, v42, s[24:25] offset:576
	global_atomic_add_f32 v131, v43, s[24:25] offset:580
	global_atomic_add_f32 v131, v44, s[24:25] offset:584
	global_atomic_add_f32 v131, v45, s[24:25] offset:588
.Lg4s_q5:
	s_cmp_lg_u32 s5, 5
	s_cbranch_scc1 .Lg4s_q6
	v_add_u32_e32 v131, 0x90000, v130
	global_atomic_add_f32 v131, v54, s[24:25]
	global_atomic_add_f32 v131, v55, s[24:25] offset:4
	global_atomic_add_f32 v131, v56, s[24:25] offset:8
	global_atomic_add_f32 v131, v57, s[24:25] offset:12
	global_atomic_add_f32 v131, v50, s[24:25] offset:64
	global_atomic_add_f32 v131, v51, s[24:25] offset:68
	global_atomic_add_f32 v131, v52, s[24:25] offset:72
	global_atomic_add_f32 v131, v53, s[24:25] offset:76
	global_atomic_add_f32 v131, v30, s[24:25] offset:512
	global_atomic_add_f32 v131, v31, s[24:25] offset:516
	global_atomic_add_f32 v131, v32, s[24:25] offset:520
	global_atomic_add_f32 v131, v33, s[24:25] offset:524
	global_atomic_add_f32 v131, v26, s[24:25] offset:576
	global_atomic_add_f32 v131, v27, s[24:25] offset:580
	global_atomic_add_f32 v131, v28, s[24:25] offset:584
	global_atomic_add_f32 v131, v29, s[24:25] offset:588
.Lg4s_q6:
	s_cmp_lg_u32 s5, 6
	s_cbranch_scc1 .Lg4s_q7
	v_add_u32_e32 v131, 0xa0000, v130
	global_atomic_add_f32 v131, v38, s[24:25]
	global_atomic_add_f32 v131, v39, s[24:25] offset:4
	global_atomic_add_f32 v131, v40, s[24:25] offset:8
	global_atomic_add_f32 v131, v41, s[24:25] offset:12
	global_atomic_add_f32 v131, v34, s[24:25] offset:64
	global_atomic_add_f32 v131, v35, s[24:25] offset:68
	global_atomic_add_f32 v131, v36, s[24:25] offset:72
	global_atomic_add_f32 v131, v37, s[24:25] offset:76
	global_atomic_add_f32 v131, v14, s[24:25] offset:512
	global_atomic_add_f32 v131, v15, s[24:25] offset:516
	global_atomic_add_f32 v131, v16, s[24:25] offset:520
	global_atomic_add_f32 v131, v17, s[24:25] offset:524
	global_atomic_add_f32 v131, v10, s[24:25] offset:576
	global_atomic_add_f32 v131, v11, s[24:25] offset:580
	global_atomic_add_f32 v131, v12, s[24:25] offset:584
	global_atomic_add_f32 v131, v13, s[24:25] offset:588
.Lg4s_q7:
	s_cmp_lg_u32 s5, 7
	s_cbranch_scc1 .Lg4s_q8
	v_add_u32_e32 v131, 0xb0000, v130
	global_atomic_add_f32 v131, v22, s[24:25]
	global_atomic_add_f32 v131, v23, s[24:25] offset:4
	global_atomic_add_f32 v131, v24, s[24:25] offset:8
	global_atomic_add_f32 v131, v25, s[24:25] offset:12
	global_atomic_add_f32 v131, v18, s[24:25] offset:64
	global_atomic_add_f32 v131, v19, s[24:25] offset:68
	global_atomic_add_f32 v131, v20, s[24:25] offset:72
	global_atomic_add_f32 v131, v21, s[24:25] offset:76
	global_atomic_add_f32 v131, v6, s[24:25] offset:512
	global_atomic_add_f32 v131, v7, s[24:25] offset:516
	global_atomic_add_f32 v131, v8, s[24:25] offset:520
	global_atomic_add_f32 v131, v9, s[24:25] offset:524
	global_atomic_add_f32 v131, v2, s[24:25] offset:576
	global_atomic_add_f32 v131, v3, s[24:25] offset:580
	global_atomic_add_f32 v131, v4, s[24:25] offset:584
	global_atomic_add_f32 v131, v5, s[24:25] offset:588
.Lg4s_q8:
	s_waitcnt vmcnt(0)
	s_cmpk_lt_u32 s28, 0x100
	s_cbranch_scc0 .LBB0_1552
	s_barrier
